# nt on once-read streams: gla_sample state quads, gla_scan kv/decay loads, g3 item tile loads
# baseline (speedup 1.0000x reference)
.LBB0_1640:
	s_lshr_b32 s16, s2, 2
	s_add_i32 s18, s16, 0x4000
	s_mul_i32 s17, s18, 0x3000
	s_mul_hi_u32 s16, s18, 0x3000
	s_add_u32 s22, s46, s17
	s_addc_u32 s23, s47, s16
	s_and_b32 s98, s2, 0x7ffffffc
	s_mov_b32 s99, s19
	s_or_b32 s98, s4, s98
	s_lshl_b64 s[98:99], s[98:99], 15
	v_lshl_add_u64 v[246:247], v[230:231], 0, s[98:99]
	v_lshl_add_u64 v[234:235], v[246:247], 0, v[18:19]
	v_lshl_add_u64 v[238:239], v[246:247], 0, v[20:21]
	v_lshl_add_u64 v[242:243], v[246:247], 0, v[22:23]
	v_lshl_add_u64 v[246:247], v[246:247], 0, v[24:25]
	s_and_saveexec_b64 s[16:17], s[6:7]
	s_cbranch_execz .Lmy_gs0_nold
	global_load_dwordx4 v[234:237], v[234:235], off nt
	global_load_dwordx4 v[238:241], v[238:239], off nt
	global_load_dwordx4 v[242:245], v[242:243], off nt
	global_load_dwordx4 v[246:249], v[246:247], off nt

.LBB0_1644:
	s_andn2_saveexec_b64 s[24:25], s[16:17]
	s_cbranch_execz .LBB0_1648
	v_mov_b32_e32 v41, s22
	s_mov_b32 s21, s19
	v_mov_b32_e32 v46, s23
	v_add_co_u32_e32 v54, vcc, 0x2000, v41
	v_lshl_add_u64 v[42:43], v[10:11], 2, s[22:23]
	v_lshl_add_u64 v[44:45], v[12:13], 2, s[22:23]
	v_addc_co_u32_e32 v55, vcc, 0, v46, vcc
	global_load_dword v41, v[42:43], off
	global_load_dword v66, v[44:45], off
	s_nop 0
	global_load_dwordx4 v[42:45], v[54:55], off offset:1120
	global_load_dwordx4 v[46:49], v[54:55], off offset:1136
	global_load_dwordx4 v[50:53], v[54:55], off offset:1152
	s_nop 0
	global_load_dwordx4 v[54:57], v[54:55], off offset:1168
	v_xor_b32_e32 v80, 32, v1
	s_waitcnt lgkmcnt(0)
	v_lshl_add_u64 v[58:59], v[232:233], 0, s[20:21]
	v_lshl_add_u64 v[60:61], v[8:9], 2, v[250:251]
	v_lshl_add_u64 v[58:59], v[130:131], 2, v[58:59]
	global_load_dword v67, v[60:61], off
	global_load_dword v68, v[58:59], off
	global_load_dword v69, v[58:59], off offset:1024
	global_load_dword v70, v[58:59], off offset:2048
	global_load_dword v71, v[58:59], off offset:3072
	v_add_co_u32_e64 v62, s[16:17], s30, v58
	v_add_co_u32_e32 v60, vcc, s31, v58
	s_nop 0
	v_addc_co_u32_e64 v63, s[16:17], 0, v59, s[16:17]
	v_add_co_u32_e64 v64, s[16:17], s29, v58
	v_addc_co_u32_e32 v61, vcc, 0, v59, vcc
	s_nop 0
	v_addc_co_u32_e64 v65, s[16:17], 0, v59, s[16:17]
	global_load_dword v58, v[62:63], off offset:-4096
	global_load_dword v59, v[60:61], off offset:1024
	global_load_dword v72, v[60:61], off offset:2048
	s_nop 0
	global_load_dword v60, v[60:61], off offset:3072
	s_nop 0
	global_load_dword v61, v[62:63], off
	global_load_dword v73, v[62:63], off offset:1024
	global_load_dword v74, v[62:63], off offset:2048
	s_nop 0
	global_load_dword v62, v[62:63], off offset:3072
	s_nop 0
	global_load_dword v63, v[64:65], off
	global_load_dword v75, v[64:65], off offset:1024
	global_load_dword v76, v[64:65], off offset:2048
	s_nop 0
	global_load_dword v64, v[64:65], off offset:3072
	global_load_dwordx4 v[234:237], v[234:235], off nt
	global_load_dwordx4 v[238:241], v[238:239], off nt
	global_load_dwordx4 v[242:245], v[242:243], off nt
	global_load_dwordx4 v[246:249], v[246:247], off nt
	v_cmp_lt_i32_e32 vcc, v36, v35
	s_waitcnt vmcnt(4)
	v_mul_f32_e32 v77, 0x3e000000, v41
	v_mul_f32_e32 v41, v77, v66
	v_cndmask_b32_e32 v65, v1, v36, vcc
	v_lshlrev_b32_e32 v65, 2, v65
	ds_bpermute_b32 v41, v65, v41
	v_cmp_lt_i32_e32 vcc, v37, v35
	s_waitcnt lgkmcnt(0)
	v_fmac_f32_e32 v41, v77, v66
	v_cndmask_b32_e32 v65, v1, v37, vcc
	v_lshlrev_b32_e32 v65, 2, v65
	ds_bpermute_b32 v65, v65, v41
	v_cmp_lt_i32_e32 vcc, v38, v35
	s_waitcnt lgkmcnt(0)
	v_add_f32_e32 v41, v41, v65
	v_cndmask_b32_e32 v78, v1, v38, vcc
	v_cmp_lt_i32_e32 vcc, v39, v35
	v_lshlrev_b32_e32 v78, 2, v78
	ds_bpermute_b32 v65, v78, v41
	v_cndmask_b32_e32 v79, v1, v39, vcc
	v_cmp_lt_i32_e32 vcc, v40, v35
	v_lshlrev_b32_e32 v79, 2, v79
	s_waitcnt lgkmcnt(0)
	v_add_f32_e32 v41, v41, v65
	v_cndmask_b32_e32 v78, v1, v40, vcc
	v_cmp_lt_i32_e32 vcc, v80, v35
	ds_bpermute_b32 v65, v79, v41
	v_lshlrev_b32_e32 v78, 2, v78
	s_waitcnt lgkmcnt(0)
	v_add_f32_e32 v41, v41, v65
	v_fmac_f32_e32 v67, v42, v68
	v_fmac_f32_e32 v67, v43, v69
	v_fmac_f32_e32 v67, v44, v70
	v_fmac_f32_e32 v67, v45, v71
	v_cndmask_b32_e32 v43, v1, v80, vcc
	v_fmac_f32_e32 v67, v46, v58
	v_fmac_f32_e32 v67, v47, v59
	v_fmac_f32_e32 v67, v48, v72
	v_fmac_f32_e32 v67, v49, v60
	v_fmac_f32_e32 v67, v50, v61
	v_fmac_f32_e32 v67, v51, v73
	v_fmac_f32_e32 v67, v52, v74
	v_fmac_f32_e32 v67, v53, v62
	v_fmac_f32_e32 v67, v54, v63
	v_fmac_f32_e32 v67, v55, v75
	v_fmac_f32_e32 v67, v56, v76
	v_fmac_f32_e32 v67, v57, v64
	v_mul_f32_e64 v42, |v67|, s33
	v_exp_f32_e32 v42, v42
	v_min_f32_e32 v45, 0, v67
	v_lshlrev_b32_e32 v43, 2, v43
	v_add_f32_e32 v42, 1.0, v42
	v_cmp_gt_f32_e32 vcc, s34, v42
	s_nop 1
	v_cndmask_b32_e64 v44, 0, 32, vcc
	v_ldexp_f32 v42, v42, v44
	v_log_f32_e32 v42, v42
	ds_bpermute_b32 v44, v78, v41
	v_cndmask_b32_e32 v46, 0, v34, vcc
	v_mul_f32_e32 v47, 0x3f317217, v42
	v_fma_f32 v47, v42, s35, -v47
	v_fmac_f32_e32 v47, 0x3377d1cf, v42
	v_fmac_f32_e32 v47, 0x3f317217, v42
	v_cmp_lt_f32_e64 vcc, |v42|, s36
	s_waitcnt lgkmcnt(0)
	v_add_f32_e32 v41, v41, v44
	v_cndmask_b32_e32 v42, v42, v47, vcc
	v_sub_f32_e32 v42, v42, v46
	v_sub_f32_e32 v42, v45, v42
	v_mul_f32_e32 v42, 0x3d800000, v42
	v_mul_f32_e32 v42, 0x3fb8aa3b, v42
	v_exp_f32_e32 v45, v42
	ds_bpermute_b32 v42, v43, v41
	v_mul_f32_e32 v43, v77, v45
	ds_write2st64_b32 v6, v43, v66 offset0:128 offset1:129
	ds_write_b32 v6, v45 offset:33280
	s_and_saveexec_b64 s[16:17], s[12:13]
	s_cbranch_execz .LBB0_1647
	s_waitcnt lgkmcnt(2)
	v_add_f32_e32 v41, v41, v42
	v_mov_b32_e32 v42, s96
	ds_write_b32 v42, v41 offset:34048

.LBB0_2957:
	s_or_b64 exec, exec, s[76:77]
	s_lshl_b32 s9, s8, 4
	s_lshl_b32 s36, s8, 6
	s_and_b32 s9, s9, 0xffffe000
	s_and_b32 s36, s36, 0x1fc0
	s_or_b32 s36, s9, s36
	s_ashr_i32 s9, s8, 31
	s_bfe_u32 s35, s8, 0x20007
	s_lshl_b64 s[44:45], s[8:9], 14
	s_lshl_b32 s37, s35, 6
	v_add_u32_e32 v2, s36, v67
	v_mov_b64_e32 v[26:27], s[12:13]
	v_lshl_add_u64 v[4:5], v[56:57], 0, s[44:45]
	v_add_u32_e32 v10, s36, v68
	v_mad_i64_i32 v[2:3], s[76:77], v2, s29, v[26:27]
	v_add_lshl_u32 v42, v55, s37, 2
	v_add_lshl_u32 v8, v66, s37, 2
	v_mov_b32_e32 v9, v43
	v_mad_i64_i32 v[10:11], s[44:45], v10, s29, v[26:27]
	v_add_co_u32_e32 v14, vcc, s30, v4
	v_lshl_add_u64 v[6:7], v[2:3], 0, v[42:43]
	v_lshl_add_u64 v[2:3], v[2:3], 0, v[8:9]
	v_lshl_add_u64 v[12:13], v[10:11], 0, v[42:43]
	v_lshl_add_u64 v[10:11], v[10:11], 0, v[8:9]
	v_addc_co_u32_e32 v15, vcc, 0, v5, vcc
	global_load_dword v34, v[4:5], off nt
	global_load_dword v35, v[6:7], off nt
	global_load_dword v36, v[2:3], off nt
	global_load_dword v37, v[12:13], off nt
	global_load_dword v38, v[10:11], off nt
	global_load_dword v39, v[14:15], off nt
	global_load_dword v40, v[14:15], off offset:2048 nt
	global_load_dword v41, v[4:5], off offset:2048 nt
	v_add_u32_e32 v2, s36, v69
	v_mad_i64_i32 v[2:3], s[44:45], v2, s29, v[26:27]
	v_add_u32_e32 v10, s36, v70
	v_add_u32_e32 v14, s36, v71
	v_lshl_add_u64 v[6:7], v[2:3], 0, v[42:43]
	v_mad_i64_i32 v[10:11], s[44:45], v10, s29, v[26:27]
	v_mad_i64_i32 v[14:15], s[44:45], v14, s29, v[26:27]
	v_add_co_u32_e32 v16, vcc, s4, v4
	v_lshl_add_u64 v[2:3], v[2:3], 0, v[8:9]
	v_lshl_add_u64 v[12:13], v[10:11], 0, v[42:43]
	v_lshl_add_u64 v[10:11], v[10:11], 0, v[8:9]
	v_addc_co_u32_e32 v17, vcc, 0, v5, vcc
	v_lshl_add_u64 v[18:19], v[14:15], 0, v[42:43]
	v_lshl_add_u64 v[14:15], v[14:15], 0, v[8:9]
	global_load_dword v60, v[6:7], off nt
	global_load_dword v61, v[2:3], off nt
	global_load_dword v62, v[12:13], off nt
	global_load_dword v63, v[10:11], off nt
	global_load_dword v64, v[16:17], off nt
	global_load_dword v65, v[18:19], off nt
	global_load_dword v106, v[14:15], off nt
	global_load_dword v107, v[16:17], off offset:2048 nt
	v_add_u32_e32 v20, s36, v72
	v_mad_i64_i32 v[20:21], s[44:45], v20, s29, v[26:27]
	v_add_u32_e32 v10, s36, v73
	v_add_u32_e32 v14, s36, v74
	v_lshl_add_u64 v[2:3], v[20:21], 0, v[42:43]
	v_mad_i64_i32 v[10:11], s[44:45], v10, s29, v[26:27]
	v_add_co_u32_e32 v4, vcc, s29, v4
	v_mad_i64_i32 v[14:15], s[44:45], v14, s29, v[26:27]
	v_lshl_add_u64 v[6:7], v[20:21], 0, v[8:9]
	v_addc_co_u32_e32 v5, vcc, 0, v5, vcc
	v_lshl_add_u64 v[12:13], v[10:11], 0, v[42:43]
	v_lshl_add_u64 v[10:11], v[10:11], 0, v[8:9]
	v_lshl_add_u64 v[16:17], v[14:15], 0, v[42:43]
	v_lshl_add_u64 v[8:9], v[14:15], 0, v[8:9]
	global_load_dword v42, v[2:3], off nt
	global_load_dword v108, v[6:7], off nt
	global_load_dword v109, v[4:5], off nt
	global_load_dword v110, v[12:13], off nt
	global_load_dword v111, v[10:11], off nt
	global_load_dword v112, v[16:17], off nt
	global_load_dword v113, v[8:9], off nt
	global_load_dword v114, v[4:5], off offset:2048 nt
	s_lshl_b64 s[8:9], s[8:9], 15
	v_add_u32_e32 v2, s36, v75
	v_lshl_add_u64 v[28:29], v[44:45], 0, s[8:9]
	v_mad_i64_i32 v[2:3], s[8:9], v2, s29, v[26:27]
	s_lshl_b32 s70, s35, 9
	v_lshl_add_u64 v[2:3], v[2:3], 0, s[70:71]
	v_mov_b32_e32 v59, v43
	v_add_u32_e32 v10, s36, v76
	v_lshl_add_u64 v[2:3], v[2:3], 0, v[58:59]
	v_mad_i64_i32 v[10:11], s[8:9], v10, s29, v[26:27]
	v_add_co_u32_e32 v2, vcc, s30, v2
	v_lshl_add_u64 v[10:11], v[10:11], 0, s[70:71]
	v_add_u32_e32 v18, s36, v77
	v_addc_co_u32_e32 v3, vcc, 0, v3, vcc
	v_lshl_add_u64 v[10:11], v[10:11], 0, v[58:59]
	v_mad_i64_i32 v[18:19], s[8:9], v18, s29, v[26:27]
	v_add_co_u32_e32 v10, vcc, s30, v10
	v_lshl_add_u64 v[18:19], v[18:19], 0, s[70:71]
	v_add_u32_e32 v30, s36, v78
	v_addc_co_u32_e32 v11, vcc, 0, v11, vcc
	v_lshl_add_u64 v[18:19], v[18:19], 0, v[58:59]
	v_mad_i64_i32 v[26:27], s[8:9], v30, s29, v[26:27]
	v_add_co_u32_e32 v18, vcc, s30, v18
	v_lshl_add_u64 v[26:27], v[26:27], 0, s[70:71]
	s_nop 0
	v_addc_co_u32_e32 v19, vcc, 0, v19, vcc
	v_lshl_add_u64 v[26:27], v[26:27], 0, v[58:59]
	v_add_co_u32_e32 v26, vcc, s30, v26
	v_lshl_add_u64 v[6:7], v[46:47], 2, v[28:29]
	v_lshl_add_u64 v[14:15], v[48:49], 2, v[28:29]
	v_lshl_add_u64 v[22:23], v[50:51], 2, v[28:29]
	v_addc_co_u32_e32 v27, vcc, 0, v27, vcc
	v_lshl_add_u64 v[30:31], v[52:53], 2, v[28:29]
	global_load_dwordx4 v[2:5], v[2:3], off offset:3168 nt
	s_nop 0
	global_load_dwordx4 v[6:9], v[6:7], off nt
	s_nop 0
	global_load_dwordx4 v[10:13], v[10:11], off offset:3168 nt
	s_nop 0
	global_load_dwordx4 v[14:17], v[14:15], off nt
	s_nop 0
	global_load_dwordx4 v[18:21], v[18:19], off offset:3168 nt
	s_nop 0
	global_load_dwordx4 v[22:25], v[22:23], off nt
	s_nop 0
	global_load_dwordx4 v[26:29], v[26:27], off offset:3168 nt
	s_nop 0
	global_load_dwordx4 v[30:33], v[30:31], off nt
	s_waitcnt vmcnt(0) lgkmcnt(0)
	v_mul_f32_e32 v59, 0x3fb8aa3b, v34
	v_mul_f32_e32 v34, 0xbfb8aa3b, v34
	v_exp_f32_e32 v34, v34
	v_exp_f32_e32 v59, v59
	v_mul_f32_e32 v35, 0x3e000000, v35
	v_mul_f32_e32 v34, v36, v34
	v_mul_f32_e32 v36, 0x3fb8aa3b, v41
	v_exp_f32_e32 v36, v36
	v_mul_f32_e32 v35, v35, v59
	v_mul_f32_e32 v41, 0xbfb8aa3b, v41
	s_barrier
	v_add_u32_e32 v232, s36, v94
	v_mov_b64_e32 v[234:235], s[12:13]
	s_lshl_b32 s98, s35, 2
	s_mov_b32 s99, 0
	v_lshlrev_b32_e32 v230, 2, v54
	v_mov_b32_e32 v231, 0
	v_mad_i64_i32 v[234:235], s[100:101], v232, s29, v[234:235]
	v_lshl_add_u64 v[234:235], v[234:235], 0, s[98:99]
	v_lshl_add_u64 v[234:235], v[234:235], 0, v[230:231]
	v_lshl_add_u64 v[234:235], v[234:235], 0, s[72:73]
	global_load_dword v236, v[234:235], off
	v_exp_f32_e32 v41, v41
	ds_write2st64_b32 v79, v35, v34 offset0:65 offset1:130
	v_mul_f32_e32 v34, 0x3e000000, v37
	v_mul_f32_e32 v34, v34, v36
	v_mul_f32_e32 v36, 0x3fb8aa3b, v39
	v_mul_f32_e32 v37, 0xbfb8aa3b, v39
	v_exp_f32_e32 v36, v36
	v_exp_f32_e32 v37, v37
	v_mul_f32_e32 v35, v38, v41
	ds_write2st64_b32 v80, v34, v35 offset0:65 offset1:130
	v_mul_f32_e32 v34, 0x3e000000, v60
	v_mul_f32_e32 v34, v34, v36
	v_mul_f32_e32 v35, v61, v37
	v_mul_f32_e32 v36, 0x3fb8aa3b, v40
	v_mul_f32_e32 v37, 0xbfb8aa3b, v40
	v_exp_f32_e32 v36, v36
	v_exp_f32_e32 v37, v37
	ds_write2st64_b32 v81, v34, v35 offset0:65 offset1:130
	v_mul_f32_e32 v34, 0x3e000000, v62
	v_mul_f32_e32 v34, v34, v36
	v_mul_f32_e32 v35, v63, v37
	v_mul_f32_e32 v36, 0x3fb8aa3b, v64
	v_mul_f32_e32 v37, 0xbfb8aa3b, v64
	v_exp_f32_e32 v36, v36
	v_exp_f32_e32 v37, v37
	ds_write2st64_b32 v82, v34, v35 offset0:65 offset1:130
	v_mul_f32_e32 v34, 0x3e000000, v65
	v_mul_f32_e32 v34, v34, v36
	v_mul_f32_e32 v35, v106, v37
	v_mul_f32_e32 v36, 0x3fb8aa3b, v107
	v_mul_f32_e32 v37, 0xbfb8aa3b, v107
	v_exp_f32_e32 v36, v36
	v_exp_f32_e32 v37, v37
	ds_write2st64_b32 v83, v34, v35 offset0:65 offset1:130
	v_mul_f32_e32 v34, 0x3e000000, v42
	v_mul_f32_e32 v34, v34, v36
	v_mul_f32_e32 v35, v108, v37
	v_mul_f32_e32 v36, 0x3fb8aa3b, v109
	v_mul_f32_e32 v37, 0xbfb8aa3b, v109
	v_exp_f32_e32 v36, v36
	v_exp_f32_e32 v37, v37
	ds_write2st64_b32 v84, v34, v35 offset0:65 offset1:130
	v_mul_f32_e32 v34, 0x3e000000, v110
	v_mul_f32_e32 v34, v34, v36
	v_mul_f32_e32 v35, v111, v37
	v_mul_f32_e32 v36, 0x3fb8aa3b, v114
	v_mul_f32_e32 v37, 0xbfb8aa3b, v114
	v_exp_f32_e32 v36, v36
	v_exp_f32_e32 v37, v37
	ds_write2st64_b32 v85, v34, v35 offset0:65 offset1:130
	v_mul_f32_e32 v34, 0x3e000000, v112
	v_mul_f32_e32 v34, v34, v36
	v_mul_f32_e32 v35, v113, v37
	ds_write2st64_b32 v86, v34, v35 offset0:65 offset1:130
	ds_write_b128 v87, v[2:5] offset:49920
	ds_write_b128 v88, v[6:9]
	ds_write_b128 v87, v[10:13] offset:58112
	ds_write_b128 v89, v[14:17]
	ds_write_b128 v90, v[18:21]
	ds_write_b128 v91, v[22:25]
	ds_write_b128 v92, v[26:29]
	ds_write_b128 v93, v[30:33]
	v_mov_b32_e32 v2, 0
	s_lshl_b32 s35, s35, 7
	s_mov_b32 s8, 32
	v_mov_b32_e32 v18, v97
	v_mov_b32_e32 v19, v96
	v_mov_b32_e32 v3, v2
	v_mov_b32_e32 v4, v2
	v_mov_b32_e32 v5, v2
	v_mov_b32_e32 v6, v2
	v_mov_b32_e32 v7, v2
	v_mov_b32_e32 v8, v2
	v_mov_b32_e32 v9, v2
	v_mov_b32_e32 v10, v2
	v_mov_b32_e32 v11, v2
	v_mov_b32_e32 v12, v2
	v_mov_b32_e32 v13, v2
	v_mov_b32_e32 v14, v2
	v_mov_b32_e32 v15, v2
	v_mov_b32_e32 v16, v2
	v_mov_b32_e32 v17, v2
	s_waitcnt lgkmcnt(0)
	s_barrier

.LBB0_4247:
	s_lshr_b32 s16, s2, 2
	s_add_i32 s18, s16, 0x4000
	s_mul_i32 s17, s18, 0x3000
	s_mul_hi_u32 s16, s18, 0x3000
	s_add_u32 s22, s46, s17
	s_addc_u32 s23, s47, s16
	s_and_b32 s98, s2, 0x7ffffffc
	s_mov_b32 s99, s19
	s_add_i32 s98, s3, s98
	s_lshl_b64 s[98:99], s[98:99], 15
	v_lshl_add_u64 v[246:247], v[230:231], 0, s[98:99]
	v_lshl_add_u64 v[234:235], v[246:247], 0, v[18:19]
	v_lshl_add_u64 v[238:239], v[246:247], 0, v[20:21]
	v_lshl_add_u64 v[242:243], v[246:247], 0, v[22:23]
	v_lshl_add_u64 v[246:247], v[246:247], 0, v[24:25]
	s_and_saveexec_b64 s[16:17], s[6:7]
	s_cbranch_execz .Lmy_gs1_nold
	global_load_dwordx4 v[234:237], v[234:235], off nt
	global_load_dwordx4 v[238:241], v[238:239], off nt
	global_load_dwordx4 v[242:245], v[242:243], off nt
	global_load_dwordx4 v[246:249], v[246:247], off nt

.LBB0_4251:
	s_andn2_saveexec_b64 s[24:25], s[16:17]
	s_cbranch_execz .LBB0_4255
	v_mov_b32_e32 v46, s22
	v_mov_b32_e32 v47, s23
	v_add_co_u32_e32 v54, vcc, 0x2000, v46
	v_lshl_add_u64 v[42:43], v[8:9], 2, s[22:23]
	v_lshl_add_u64 v[44:45], v[10:11], 2, s[22:23]
	v_addc_co_u32_e32 v55, vcc, 0, v47, vcc
	global_load_dword v66, v[42:43], off
	global_load_dword v67, v[44:45], off
	s_nop 0
	global_load_dwordx4 v[42:45], v[54:55], off offset:1120
	global_load_dwordx4 v[46:49], v[54:55], off offset:1136
	global_load_dwordx4 v[50:53], v[54:55], off offset:1152
	s_nop 0
	global_load_dwordx4 v[54:57], v[54:55], off offset:1168
	s_mov_b32 s21, s19
	s_waitcnt lgkmcnt(0)
	v_lshl_add_u64 v[58:59], v[232:233], 0, s[20:21]
	v_lshl_add_u64 v[60:61], v[16:17], 2, v[250:251]
	global_load_dword v68, v[60:61], off offset:1024
	v_lshl_add_u64 v[58:59], v[130:131], 2, v[58:59]
	v_add_co_u32_e32 v60, vcc, s28, v58
	v_add_co_u32_e64 v62, s[16:17], s30, v58
	s_nop 0
	v_addc_co_u32_e32 v61, vcc, 0, v59, vcc
	v_addc_co_u32_e64 v63, s[16:17], 0, v59, s[16:17]
	v_add_co_u32_e64 v64, s[16:17], s31, v58
	v_add_co_u32_e32 v58, vcc, s29, v58
	s_nop 0
	v_addc_co_u32_e64 v65, s[16:17], 0, v59, s[16:17]
	v_addc_co_u32_e32 v59, vcc, 0, v59, vcc
	global_load_dword v69, v[58:59], off offset:-4096
	global_load_dword v70, v[60:61], off offset:1024
	global_load_dword v71, v[60:61], off offset:2048
	s_nop 0
	global_load_dword v60, v[60:61], off offset:3072
	s_nop 0
	global_load_dword v61, v[58:59], off
	global_load_dword v72, v[58:59], off offset:1024
	global_load_dword v73, v[58:59], off offset:2048
	s_nop 0
	global_load_dword v58, v[58:59], off offset:3072
	s_nop 0
	global_load_dword v59, v[64:65], off offset:-4096
	global_load_dword v74, v[62:63], off offset:1024
	global_load_dword v75, v[62:63], off offset:2048
	s_nop 0
	global_load_dword v62, v[62:63], off offset:3072
	s_nop 0
	global_load_dword v63, v[64:65], off
	global_load_dword v76, v[64:65], off offset:1024
	global_load_dword v77, v[64:65], off offset:2048
	s_nop 0
	global_load_dword v64, v[64:65], off offset:3072
	global_load_dwordx4 v[234:237], v[234:235], off nt
	global_load_dwordx4 v[238:241], v[238:239], off nt
	global_load_dwordx4 v[242:245], v[242:243], off nt
	global_load_dwordx4 v[246:249], v[246:247], off nt
	v_cmp_lt_i32_e32 vcc, v36, v35
	s_waitcnt vmcnt(4)
	v_mul_f32_e32 v66, 0x3e000000, v66
	v_mul_f32_e32 v78, v66, v67
	v_cndmask_b32_e32 v65, v1, v36, vcc
	v_lshlrev_b32_e32 v65, 2, v65
	ds_bpermute_b32 v65, v65, v78
	v_cmp_lt_i32_e32 vcc, v37, v35
	s_waitcnt lgkmcnt(0)
	v_fmac_f32_e32 v65, v66, v67
	v_cndmask_b32_e32 v78, v1, v37, vcc
	v_lshlrev_b32_e32 v78, 2, v78
	ds_bpermute_b32 v78, v78, v65
	v_cmp_lt_i32_e32 vcc, v38, v35
	s_waitcnt lgkmcnt(0)
	v_add_f32_e32 v65, v65, v78
	v_cndmask_b32_e32 v79, v1, v38, vcc
	v_cmp_lt_i32_e32 vcc, v39, v35
	v_lshlrev_b32_e32 v79, 2, v79
	ds_bpermute_b32 v78, v79, v65
	v_cndmask_b32_e32 v80, v1, v39, vcc
	v_cmp_lt_i32_e32 vcc, v40, v35
	v_lshlrev_b32_e32 v80, 2, v80
	s_waitcnt lgkmcnt(0)
	v_add_f32_e32 v65, v65, v78
	v_cndmask_b32_e32 v79, v1, v40, vcc
	v_cmp_lt_i32_e32 vcc, v41, v35
	ds_bpermute_b32 v78, v80, v65
	v_fmac_f32_e32 v68, v42, v69
	v_fmac_f32_e32 v68, v43, v70
	v_fmac_f32_e32 v68, v44, v71
	v_fmac_f32_e32 v68, v45, v60
	v_fmac_f32_e32 v68, v46, v61
	v_fmac_f32_e32 v68, v47, v72
	v_fmac_f32_e32 v68, v48, v73
	v_fmac_f32_e32 v68, v49, v58
	v_fmac_f32_e32 v68, v50, v59
	v_fmac_f32_e32 v68, v51, v74
	v_fmac_f32_e32 v68, v52, v75
	v_fmac_f32_e32 v68, v53, v62
	v_fmac_f32_e32 v68, v54, v63
	v_fmac_f32_e32 v68, v55, v76
	v_fmac_f32_e32 v68, v56, v77
	v_fmac_f32_e32 v68, v57, v64
	v_mul_f32_e64 v42, |v68|, s33
	v_exp_f32_e32 v42, v42
	v_cndmask_b32_e32 v81, v1, v41, vcc
	v_lshlrev_b32_e32 v43, 2, v79
	s_waitcnt lgkmcnt(0)
	v_add_f32_e32 v45, v65, v78
	v_add_f32_e32 v42, 1.0, v42
	v_cmp_gt_f32_e32 vcc, s34, v42
	ds_bpermute_b32 v43, v43, v45
	v_lshlrev_b32_e32 v44, 2, v81
	v_cndmask_b32_e64 v46, 0, 32, vcc
	v_ldexp_f32 v42, v42, v46
	v_log_f32_e32 v42, v42
	v_cndmask_b32_e32 v47, 0, v34, vcc
	v_min_f32_e32 v46, 0, v68
	v_mul_f32_e32 v48, 0x3f317217, v42
	v_fma_f32 v48, v42, s35, -v48
	v_fmac_f32_e32 v48, 0x3377d1cf, v42
	v_fmac_f32_e32 v48, 0x3f317217, v42
	v_cmp_lt_f32_e64 vcc, |v42|, s36
	s_nop 1
	v_cndmask_b32_e32 v42, v42, v48, vcc
	v_sub_f32_e32 v42, v42, v47
	v_sub_f32_e32 v42, v46, v42
	v_mul_f32_e32 v42, 0x3d800000, v42
	v_mul_f32_e32 v42, 0x3fb8aa3b, v42
	v_exp_f32_e32 v46, v42
	s_waitcnt lgkmcnt(0)
	v_add_f32_e32 v42, v45, v43
	ds_bpermute_b32 v43, v44, v42
	v_mul_f32_e32 v44, v66, v46
	ds_write2st64_b32 v6, v44, v67 offset0:128 offset1:129
	ds_write_b32 v6, v46 offset:33280
	s_and_saveexec_b64 s[16:17], s[12:13]
	s_cbranch_execz .LBB0_4254
	s_waitcnt lgkmcnt(2)
	v_add_f32_e32 v42, v42, v43
	v_mov_b32_e32 v43, s94
	ds_write_b32 v43, v42 offset:34048

.LBB0_5564:
	s_or_b64 exec, exec, s[76:77]
	s_lshl_b32 s9, s8, 4
	s_lshl_b32 s36, s8, 6
	s_and_b32 s9, s9, 0xffffe000
	s_and_b32 s36, s36, 0x1fc0
	s_or_b32 s36, s9, s36
	s_ashr_i32 s9, s8, 31
	s_bfe_u32 s35, s8, 0x20007
	s_lshl_b64 s[42:43], s[8:9], 14
	s_lshl_b32 s37, s35, 6
	v_add_u32_e32 v2, s36, v67
	v_mov_b64_e32 v[26:27], s[12:13]
	v_lshl_add_u64 v[4:5], v[56:57], 0, s[42:43]
	v_add_u32_e32 v10, s36, v68
	v_mad_i64_i32 v[2:3], s[44:45], v2, s29, v[26:27]
	v_add_lshl_u32 v42, v55, s37, 2
	v_add_lshl_u32 v8, v66, s37, 2
	v_mov_b32_e32 v9, v43
	v_mad_i64_i32 v[10:11], s[42:43], v10, s29, v[26:27]
	v_add_co_u32_e32 v14, vcc, s30, v4
	v_lshl_add_u64 v[6:7], v[2:3], 0, v[42:43]
	v_lshl_add_u64 v[2:3], v[2:3], 0, v[8:9]
	v_lshl_add_u64 v[12:13], v[10:11], 0, v[42:43]
	v_lshl_add_u64 v[10:11], v[10:11], 0, v[8:9]
	v_addc_co_u32_e32 v15, vcc, 0, v5, vcc
	global_load_dword v34, v[4:5], off nt
	global_load_dword v35, v[6:7], off nt
	global_load_dword v36, v[2:3], off nt
	global_load_dword v37, v[12:13], off nt
	global_load_dword v38, v[10:11], off nt
	global_load_dword v39, v[14:15], off nt
	global_load_dword v40, v[14:15], off offset:2048 nt
	global_load_dword v41, v[4:5], off offset:2048 nt
	v_add_u32_e32 v2, s36, v69
	v_mad_i64_i32 v[2:3], s[42:43], v2, s29, v[26:27]
	v_add_u32_e32 v10, s36, v70
	v_add_u32_e32 v14, s36, v71
	v_lshl_add_u64 v[6:7], v[2:3], 0, v[42:43]
	v_mad_i64_i32 v[10:11], s[42:43], v10, s29, v[26:27]
	v_mad_i64_i32 v[14:15], s[42:43], v14, s29, v[26:27]
	v_add_co_u32_e32 v16, vcc, s28, v4
	v_lshl_add_u64 v[2:3], v[2:3], 0, v[8:9]
	v_lshl_add_u64 v[12:13], v[10:11], 0, v[42:43]
	v_lshl_add_u64 v[10:11], v[10:11], 0, v[8:9]
	v_addc_co_u32_e32 v17, vcc, 0, v5, vcc
	v_lshl_add_u64 v[18:19], v[14:15], 0, v[42:43]
	v_lshl_add_u64 v[14:15], v[14:15], 0, v[8:9]
	global_load_dword v60, v[6:7], off nt
	global_load_dword v61, v[2:3], off nt
	global_load_dword v62, v[12:13], off nt
	global_load_dword v63, v[10:11], off nt
	global_load_dword v64, v[16:17], off nt
	global_load_dword v65, v[18:19], off nt
	global_load_dword v106, v[14:15], off nt
	global_load_dword v107, v[16:17], off offset:2048 nt
	v_add_u32_e32 v20, s36, v72
	v_mad_i64_i32 v[20:21], s[42:43], v20, s29, v[26:27]
	v_add_u32_e32 v10, s36, v73
	v_add_u32_e32 v14, s36, v74
	v_lshl_add_u64 v[2:3], v[20:21], 0, v[42:43]
	v_mad_i64_i32 v[10:11], s[42:43], v10, s29, v[26:27]
	v_add_co_u32_e32 v4, vcc, s29, v4
	v_mad_i64_i32 v[14:15], s[42:43], v14, s29, v[26:27]
	v_lshl_add_u64 v[6:7], v[20:21], 0, v[8:9]
	v_addc_co_u32_e32 v5, vcc, 0, v5, vcc
	v_lshl_add_u64 v[12:13], v[10:11], 0, v[42:43]
	v_lshl_add_u64 v[10:11], v[10:11], 0, v[8:9]
	v_lshl_add_u64 v[16:17], v[14:15], 0, v[42:43]
	v_lshl_add_u64 v[8:9], v[14:15], 0, v[8:9]
	global_load_dword v42, v[2:3], off nt
	global_load_dword v108, v[6:7], off nt
	global_load_dword v109, v[4:5], off nt
	global_load_dword v110, v[12:13], off nt
	global_load_dword v111, v[10:11], off nt
	global_load_dword v112, v[16:17], off nt
	global_load_dword v113, v[8:9], off nt
	global_load_dword v114, v[4:5], off offset:2048 nt
	s_lshl_b64 s[8:9], s[8:9], 15
	v_add_u32_e32 v2, s36, v75
	v_lshl_add_u64 v[28:29], v[44:45], 0, s[8:9]
	v_mad_i64_i32 v[2:3], s[8:9], v2, s29, v[26:27]
	s_lshl_b32 s70, s35, 9
	v_lshl_add_u64 v[2:3], v[2:3], 0, s[70:71]
	v_mov_b32_e32 v59, v43
	v_add_u32_e32 v10, s36, v76
	v_lshl_add_u64 v[2:3], v[2:3], 0, v[58:59]
	v_mad_i64_i32 v[10:11], s[8:9], v10, s29, v[26:27]
	v_add_co_u32_e32 v2, vcc, s30, v2
	v_lshl_add_u64 v[10:11], v[10:11], 0, s[70:71]
	v_add_u32_e32 v18, s36, v77
	v_addc_co_u32_e32 v3, vcc, 0, v3, vcc
	v_lshl_add_u64 v[10:11], v[10:11], 0, v[58:59]
	v_mad_i64_i32 v[18:19], s[8:9], v18, s29, v[26:27]
	v_add_co_u32_e32 v10, vcc, s30, v10
	v_lshl_add_u64 v[18:19], v[18:19], 0, s[70:71]
	v_add_u32_e32 v30, s36, v78
	v_addc_co_u32_e32 v11, vcc, 0, v11, vcc
	v_lshl_add_u64 v[18:19], v[18:19], 0, v[58:59]
	v_mad_i64_i32 v[26:27], s[8:9], v30, s29, v[26:27]
	v_add_co_u32_e32 v18, vcc, s30, v18
	v_lshl_add_u64 v[26:27], v[26:27], 0, s[70:71]
	s_nop 0
	v_addc_co_u32_e32 v19, vcc, 0, v19, vcc
	v_lshl_add_u64 v[26:27], v[26:27], 0, v[58:59]
	v_add_co_u32_e32 v26, vcc, s30, v26
	v_lshl_add_u64 v[6:7], v[46:47], 2, v[28:29]
	v_lshl_add_u64 v[14:15], v[48:49], 2, v[28:29]
	v_lshl_add_u64 v[22:23], v[50:51], 2, v[28:29]
	v_addc_co_u32_e32 v27, vcc, 0, v27, vcc
	v_lshl_add_u64 v[30:31], v[52:53], 2, v[28:29]
	global_load_dwordx4 v[2:5], v[2:3], off offset:3168 nt
	s_nop 0
	global_load_dwordx4 v[6:9], v[6:7], off nt
	s_nop 0
	global_load_dwordx4 v[10:13], v[10:11], off offset:3168 nt
	s_nop 0
	global_load_dwordx4 v[14:17], v[14:15], off nt
	s_nop 0
	global_load_dwordx4 v[18:21], v[18:19], off offset:3168 nt
	s_nop 0
	global_load_dwordx4 v[22:25], v[22:23], off nt
	s_nop 0
	global_load_dwordx4 v[26:29], v[26:27], off offset:3168 nt
	s_nop 0
	global_load_dwordx4 v[30:33], v[30:31], off nt
	s_waitcnt vmcnt(0) lgkmcnt(0)
	v_mul_f32_e32 v59, 0x3fb8aa3b, v34
	v_mul_f32_e32 v34, 0xbfb8aa3b, v34
	v_exp_f32_e32 v34, v34
	v_exp_f32_e32 v59, v59
	v_mul_f32_e32 v35, 0x3e000000, v35
	v_mul_f32_e32 v34, v36, v34
	v_mul_f32_e32 v36, 0x3fb8aa3b, v41
	v_exp_f32_e32 v36, v36
	v_mul_f32_e32 v35, v35, v59
	v_mul_f32_e32 v41, 0xbfb8aa3b, v41
	s_barrier
	v_add_u32_e32 v232, s36, v94
	v_mov_b64_e32 v[234:235], s[12:13]
	s_lshl_b32 s98, s35, 2
	s_mov_b32 s99, 0
	v_lshlrev_b32_e32 v230, 2, v54
	v_mov_b32_e32 v231, 0
	v_mad_i64_i32 v[234:235], s[100:101], v232, s29, v[234:235]
	v_lshl_add_u64 v[234:235], v[234:235], 0, s[98:99]
	v_lshl_add_u64 v[234:235], v[234:235], 0, v[230:231]
	v_lshl_add_u64 v[234:235], v[234:235], 0, s[72:73]
	global_load_dword v236, v[234:235], off
	v_exp_f32_e32 v41, v41
	ds_write2st64_b32 v79, v35, v34 offset0:65 offset1:130
	v_mul_f32_e32 v34, 0x3e000000, v37
	v_mul_f32_e32 v34, v34, v36
	v_mul_f32_e32 v36, 0x3fb8aa3b, v39
	v_mul_f32_e32 v37, 0xbfb8aa3b, v39
	v_exp_f32_e32 v36, v36
	v_exp_f32_e32 v37, v37
	v_mul_f32_e32 v35, v38, v41
	ds_write2st64_b32 v80, v34, v35 offset0:65 offset1:130
	v_mul_f32_e32 v34, 0x3e000000, v60
	v_mul_f32_e32 v34, v34, v36
	v_mul_f32_e32 v35, v61, v37
	v_mul_f32_e32 v36, 0x3fb8aa3b, v40
	v_mul_f32_e32 v37, 0xbfb8aa3b, v40
	v_exp_f32_e32 v36, v36
	v_exp_f32_e32 v37, v37
	ds_write2st64_b32 v81, v34, v35 offset0:65 offset1:130
	v_mul_f32_e32 v34, 0x3e000000, v62
	v_mul_f32_e32 v34, v34, v36
	v_mul_f32_e32 v35, v63, v37
	v_mul_f32_e32 v36, 0x3fb8aa3b, v64
	v_mul_f32_e32 v37, 0xbfb8aa3b, v64
	v_exp_f32_e32 v36, v36
	v_exp_f32_e32 v37, v37
	ds_write2st64_b32 v82, v34, v35 offset0:65 offset1:130
	v_mul_f32_e32 v34, 0x3e000000, v65
	v_mul_f32_e32 v34, v34, v36
	v_mul_f32_e32 v35, v106, v37
	v_mul_f32_e32 v36, 0x3fb8aa3b, v107
	v_mul_f32_e32 v37, 0xbfb8aa3b, v107
	v_exp_f32_e32 v36, v36
	v_exp_f32_e32 v37, v37
	ds_write2st64_b32 v83, v34, v35 offset0:65 offset1:130
	v_mul_f32_e32 v34, 0x3e000000, v42
	v_mul_f32_e32 v34, v34, v36
	v_mul_f32_e32 v35, v108, v37
	v_mul_f32_e32 v36, 0x3fb8aa3b, v109
	v_mul_f32_e32 v37, 0xbfb8aa3b, v109
	v_exp_f32_e32 v36, v36
	v_exp_f32_e32 v37, v37
	ds_write2st64_b32 v84, v34, v35 offset0:65 offset1:130
	v_mul_f32_e32 v34, 0x3e000000, v110
	v_mul_f32_e32 v34, v34, v36
	v_mul_f32_e32 v35, v111, v37
	v_mul_f32_e32 v36, 0x3fb8aa3b, v114
	v_mul_f32_e32 v37, 0xbfb8aa3b, v114
	v_exp_f32_e32 v36, v36
	v_exp_f32_e32 v37, v37
	ds_write2st64_b32 v85, v34, v35 offset0:65 offset1:130
	v_mul_f32_e32 v34, 0x3e000000, v112
	v_mul_f32_e32 v34, v34, v36
	v_mul_f32_e32 v35, v113, v37
	ds_write2st64_b32 v86, v34, v35 offset0:65 offset1:130
	ds_write_b128 v87, v[2:5] offset:49920
	ds_write_b128 v88, v[6:9]
	ds_write_b128 v87, v[10:13] offset:58112
	ds_write_b128 v89, v[14:17]
	ds_write_b128 v90, v[18:21]
	ds_write_b128 v91, v[22:25]
	ds_write_b128 v92, v[26:29]
	ds_write_b128 v93, v[30:33]
	v_mov_b32_e32 v2, 0
	s_lshl_b32 s35, s35, 7
	s_mov_b32 s8, 32
	v_mov_b32_e32 v18, v97
	v_mov_b32_e32 v19, v96
	v_mov_b32_e32 v3, v2
	v_mov_b32_e32 v4, v2
	v_mov_b32_e32 v5, v2
	v_mov_b32_e32 v6, v2
	v_mov_b32_e32 v7, v2
	v_mov_b32_e32 v8, v2
	v_mov_b32_e32 v9, v2
	v_mov_b32_e32 v10, v2
	v_mov_b32_e32 v11, v2
	v_mov_b32_e32 v12, v2
	v_mov_b32_e32 v13, v2
	v_mov_b32_e32 v14, v2
	v_mov_b32_e32 v15, v2
	v_mov_b32_e32 v16, v2
	v_mov_b32_e32 v17, v2
	s_waitcnt lgkmcnt(0)
	s_barrier
